# resid gemm80 loop: 3 compact LDS stages (80 KiB LDS, barrier words in VGPR lanes), tile k+3 in flight
# speedup vs baseline: 1.0397x; 1.0054x over previous
.LBB0_3:
	s_or_b64 exec, exec, s[8:9]
	s_load_dwordx2 s[2:3], s[0:1], 0x120
	s_waitcnt lgkmcnt(0)
	s_barrier
	v_writelane_b32 v251, s2, 3
	s_cmp_ge_i32 s2, s3
	s_nop 0
	v_writelane_b32 v251, s3, 4
	s_cbranch_scc1 .LBB0_521
	s_cmpk_gt_u32 s26, 0x1ff
	s_load_dwordx16 s[4:19], s[0:1], 0x0
	s_load_dwordx16 s[84:99], s[0:1], 0x40
	s_load_dwordx16 s[36:51], s[0:1], 0x80
	s_load_dwordx16 s[52:67], s[0:1], 0xc0
	s_cselect_b64 s[0:1], -1, 0
	v_writelane_b32 v251, s0, 5
	s_movk_i32 s3, 0x11b8
	v_lshrrev_b32_e32 v1, 20, v0
	v_writelane_b32 v251, s1, 6
	s_and_b64 s[0:1], s[0:1], exec
	s_cselect_b32 s24, s3, 0x2370
	s_add_i32 s0, s24, 0xc3
	v_writelane_b32 v251, s0, 7
	v_lshrrev_b32_e32 v0, 10, v0
	v_readlane_b32 s25, v251, 0
	s_cmp_lt_i32 s25, s0
	s_cselect_b64 s[0:1], -1, 0
	v_writelane_b32 v251, s0, 8
	v_or_b32_e32 v0, v0, v1
	s_mov_b32 s29, 0
	v_writelane_b32 v251, s1, 9
	s_not_b32 s0, s24
	v_writelane_b32 v251, s0, 10
	s_add_u32 s0, s82, 0x475c000
	s_addc_u32 s1, s83, 0
	s_add_u32 s22, s82, 0x4720000
	s_addc_u32 s23, s83, 0
	v_writelane_b32 v251, s22, 11
	s_add_u32 s3, s82, 0x3720000
	v_mov_b32_e32 v129, 0
	v_writelane_b32 v251, s23, 12
	v_writelane_b32 v251, s3, 13
	s_addc_u32 s3, s83, 0
	v_writelane_b32 v251, s3, 14
	s_add_u32 s3, s82, 0x2720000
	v_writelane_b32 v251, s3, 15
	s_addc_u32 s3, s83, 0
	v_writelane_b32 v251, s3, 16
	s_add_u32 s3, s82, 0x2320000
	v_writelane_b32 v251, s3, 17
	s_addc_u32 s3, s83, 0
	v_writelane_b32 v251, s3, 18
	s_add_u32 s3, s82, 0x1d20000
	v_writelane_b32 v251, s3, 19
	s_addc_u32 s3, s83, 0
	v_writelane_b32 v251, s3, 20
	s_add_u32 s3, s82, 0x1c20000
	v_writelane_b32 v251, s3, 21
	s_addc_u32 s3, s83, 0
	v_writelane_b32 v251, s3, 22
	s_add_u32 s3, s82, 0x1b00000
	v_writelane_b32 v251, s3, 23
	s_addc_u32 s3, s83, 0
	s_add_u32 s70, s82, 0x5160000
	s_addc_u32 s71, s83, 0
	s_cmpk_lt_i32 s25, 0x500
	v_writelane_b32 v251, s3, 24
	s_cselect_b64 s[22:23], -1, 0
	v_writelane_b32 v251, s22, 25
	s_mov_b32 s28, s29
	s_movk_i32 s2, 0x3ff
	v_writelane_b32 v251, s23, 26
	s_add_u32 s22, s82, 0x4760000
	s_addc_u32 s23, s83, 0
	v_writelane_b32 v251, s22, 27
	s_cmpk_gt_i32 s25, 0xff
	s_movk_i32 s33, 0x104
	v_writelane_b32 v251, s23, 28
	s_cselect_b64 s[22:23], -1, 0
	v_writelane_b32 v251, s22, 29
	s_add_i32 s3, s25, 0xffffff00
	v_mov_b32_e32 v209, 0x358637bd
	v_writelane_b32 v251, s23, 30
	v_writelane_b32 v251, s3, 31
	s_add_i32 s3, s26, 0xffffff00
	s_add_u32 s22, s78, 0x1000000
	v_writelane_b32 v251, s3, 32
	s_addc_u32 s23, s79, 0
	v_writelane_b32 v251, s22, 33
	v_not_b32_e32 v213, 63
	v_mov_b32_e32 v215, 0x41b17218
	v_writelane_b32 v251, s23, 34
	s_add_u32 s22, s82, 0x3f20000
	s_addc_u32 s23, s83, 0
	v_writelane_b32 v251, s22, 35
	v_mov_b32_e32 v250, 0xd55c000
	v_mov_b32_e32 v214, 0x3eb60549
	v_writelane_b32 v251, s23, 36
	s_add_u32 s22, s76, 0x1000000
	s_addc_u32 s23, s77, 0
	v_writelane_b32 v251, s22, 37
	v_mov_b32_e32 v222, 0x3e4ccccd
	v_mov_b32_e32 v223, 0x42800000
	v_writelane_b32 v251, s23, 38
	s_add_u32 s22, s82, 0x2f20000
	s_addc_u32 s23, s83, 0
	v_writelane_b32 v251, s22, 39
	v_mov_b32_e32 v228, v129
	v_mov_b32_e32 v229, v129
	v_writelane_b32 v251, s23, 40
	s_waitcnt lgkmcnt(0)
	s_add_u32 s22, s66, 0x400000
	s_addc_u32 s23, s67, 0
	v_writelane_b32 v251, s22, 41
	v_mov_b32_e32 v230, v129
	v_mov_b32_e32 v231, v129
	v_writelane_b32 v251, s23, 42
	s_add_u32 s22, s82, 0x2520000
	s_addc_u32 s23, s83, 0
	v_writelane_b32 v251, s22, 43
	v_mov_b32_e32 v130, 0x10000
	v_mov_b32_e32 v132, 0x10004
	v_writelane_b32 v251, s23, 44
	s_add_u32 s22, s64, 0x200000
	s_addc_u32 s23, s65, 0
	v_writelane_b32 v251, s22, 45
	s_nop 1
	v_writelane_b32 v251, s23, 46
	s_add_u32 s22, s82, 0x2220000
	s_addc_u32 s23, s83, 0
	v_writelane_b32 v251, s22, 47
	s_nop 1
	v_writelane_b32 v251, s23, 48
	s_add_u32 s22, s62, 0x200000
	s_addc_u32 s23, s63, 0
	v_writelane_b32 v251, s22, 49
	s_nop 1
	v_writelane_b32 v251, s23, 50
	s_add_u32 s22, s82, 0x2120000
	s_addc_u32 s23, s83, 0
	v_writelane_b32 v251, s22, 51
	s_nop 1
	v_writelane_b32 v251, s23, 52
	s_add_u32 s22, s60, 0x200000
	v_writelane_b32 v251, s52, 53
	s_addc_u32 s23, s61, 0
	s_nop 0
	v_writelane_b32 v252, s63, 0
	v_writelane_b32 v252, s64, 1
	v_writelane_b32 v252, s65, 2
	v_writelane_b32 v252, s66, 3
	v_writelane_b32 v252, s67, 4
	v_writelane_b32 v252, s22, 5
	v_writelane_b32 v251, s53, 54
	v_writelane_b32 v251, s54, 55
	v_writelane_b32 v252, s23, 6
	s_add_u32 s22, s82, 0x2020000
	s_addc_u32 s23, s83, 0
	v_writelane_b32 v252, s22, 7
	v_writelane_b32 v251, s55, 56
	v_writelane_b32 v251, s56, 57
	v_writelane_b32 v252, s23, 8
	s_add_u32 s22, s46, 0x80000
	s_addc_u32 s23, s47, 0
	v_writelane_b32 v252, s22, 9
	v_writelane_b32 v251, s57, 58
	v_writelane_b32 v251, s58, 59
	v_writelane_b32 v252, s23, 10
	s_add_u32 s22, s82, 0x1ce0000
	s_addc_u32 s23, s83, 0
	v_writelane_b32 v252, s22, 11
	v_writelane_b32 v251, s59, 60
	v_writelane_b32 v251, s60, 61
	v_writelane_b32 v252, s23, 12
	s_add_u32 s22, s44, 0x80000
	s_addc_u32 s23, s45, 0
	v_writelane_b32 v252, s22, 13
	v_writelane_b32 v251, s61, 62
	v_writelane_b32 v251, s62, 63
	v_writelane_b32 v252, s23, 14
	s_add_u32 s22, s82, 0x1ca0000
	s_addc_u32 s23, s83, 0
	v_writelane_b32 v252, s22, 15
	s_nop 1
	v_writelane_b32 v252, s23, 16
	s_add_u32 s22, s42, 0x120000
	s_addc_u32 s23, s43, 0
	v_writelane_b32 v252, s22, 17
	s_nop 1
	v_writelane_b32 v252, s23, 18
	s_add_u32 s22, s82, 0x1b90000
	s_addc_u32 s23, s83, 0
	v_writelane_b32 v252, s22, 19
	s_nop 1
	v_writelane_b32 v252, s23, 20
	s_add_u32 s22, s38, 0x600
	v_writelane_b32 v252, s36, 21
	s_addc_u32 s23, s39, 0
	s_nop 0
	v_writelane_b32 v252, s37, 22
	v_writelane_b32 v252, s38, 23
	v_writelane_b32 v252, s39, 24
	v_writelane_b32 v252, s40, 25
	v_writelane_b32 v252, s41, 26
	v_writelane_b32 v252, s42, 27
	v_writelane_b32 v252, s43, 28
	v_writelane_b32 v252, s44, 29
	v_writelane_b32 v252, s45, 30
	v_writelane_b32 v252, s46, 31
	v_writelane_b32 v252, s47, 32
	v_writelane_b32 v252, s48, 33
	v_writelane_b32 v252, s49, 34
	v_writelane_b32 v252, s50, 35
	v_writelane_b32 v252, s51, 36
	v_writelane_b32 v252, s22, 37
	s_mov_b64 s[42:43], s[0:1]
	s_add_u32 s0, s94, 0x1ac0000
	v_writelane_b32 v252, s23, 38
	v_writelane_b32 v252, s84, 39
	s_addc_u32 s1, s95, 0
	s_mul_i32 s22, s26, 12
	v_writelane_b32 v252, s85, 40
	v_writelane_b32 v252, s86, 41
	v_writelane_b32 v252, s87, 42
	v_writelane_b32 v252, s88, 43
	v_writelane_b32 v252, s89, 44
	v_writelane_b32 v252, s90, 45
	v_writelane_b32 v252, s91, 46
	v_writelane_b32 v252, s92, 47
	v_writelane_b32 v252, s93, 48
	v_writelane_b32 v252, s94, 49
	v_writelane_b32 v252, s95, 50
	v_writelane_b32 v252, s96, 51
	v_writelane_b32 v252, s97, 52
	v_writelane_b32 v252, s98, 53
	v_writelane_b32 v252, s99, 54
	v_writelane_b32 v252, s0, 55
	s_mov_b32 s36, 0x3f803f80
	s_mov_b32 s37, s36
	v_writelane_b32 v252, s1, 56
	s_add_u32 s0, s82, 0xd80000
	s_addc_u32 s1, s83, 0
	v_writelane_b32 v252, s0, 57
	s_mov_b32 s38, s36
	s_mov_b32 s39, s36
	v_writelane_b32 v252, s1, 58
	s_add_u32 s0, s82, 0xc65c000
	v_writelane_b32 v252, s0, 59
	s_addc_u32 s0, s83, 0
	s_cmpk_lt_i32 s25, 0x200
	v_writelane_b32 v252, s0, 60
	s_cselect_b64 s[0:1], -1, 0
	v_writelane_b32 v252, s0, 61
	s_movk_i32 s85, 0x1000
	s_nop 0
	v_writelane_b32 v252, s1, 62
	s_add_u32 s0, s82, 0xe461000
	s_addc_u32 s1, s83, 0
	v_writelane_b32 v252, s0, 63
	s_cmpk_lt_i32 s25, 0x280
	s_nop 0
	v_writelane_b32 v253, s1, 0
	s_cselect_b64 s[0:1], -1, 0
	v_writelane_b32 v253, s0, 1
	s_nop 1
	v_writelane_b32 v253, s1, 2
	s_add_u32 s0, s82, 0x94e0000
	s_addc_u32 s1, s83, 0
	v_writelane_b32 v253, s0, 3
	s_nop 1
	v_writelane_b32 v253, s1, 4
	s_add_u32 s0, s82, 0xa9d4000
	v_writelane_b32 v253, s0, 5
	s_addc_u32 s0, s83, 0
	v_writelane_b32 v253, s0, 6
	s_add_u32 s0, s82, 0xd55c000
	v_writelane_b32 v253, s0, 7
	s_addc_u32 s0, s83, 0
	v_writelane_b32 v253, s0, 8
	s_add_u32 s0, s82, 0xb1b4000
	v_writelane_b32 v253, s0, 9
	s_addc_u32 s0, s83, 0
	v_writelane_b32 v253, s0, 10
	s_add_u32 s0, s82, 0xb6f4000
	s_addc_u32 s1, s83, 0
	s_add_i32 s3, s26, 0xfffffec0
	v_writelane_b32 v253, s0, 11
	s_cmpk_lt_i32 s25, 0x140
	s_nop 0
	v_writelane_b32 v253, s1, 12
	s_cselect_b64 s[0:1], -1, 0
	v_writelane_b32 v253, s0, 13
	s_nop 1
	v_writelane_b32 v253, s1, 14
	s_and_b64 s[0:1], s[0:1], exec
	s_cselect_b32 s0, 0x100000, s3
	s_cmpk_gt_i32 s26, 0x1bf
	s_cselect_b32 s3, s0, s26
	s_cmpk_lt_i32 s25, 0x300
	s_cselect_b64 s[0:1], -1, 0
	v_writelane_b32 v253, s0, 15
	s_nop 1
	v_writelane_b32 v253, s1, 16
	s_add_u32 s0, s82, 0x9f54000
	s_addc_u32 s1, s83, 0
	v_writelane_b32 v253, s0, 17
	s_nop 1
	v_writelane_b32 v253, s1, 18
	s_add_u32 s0, s82, 0x9f00000
	s_addc_u32 s1, s83, 0
	v_writelane_b32 v253, s0, 19
	s_nop 1
	v_writelane_b32 v253, s1, 20
	s_add_u32 s0, s82, 0xe45c000
	s_addc_u32 s1, s83, 0
	v_writelane_b32 v253, s0, 21
	s_nop 1
	v_writelane_b32 v253, s1, 22
	s_add_u32 s0, s82, 0x475c040
	s_addc_u32 s1, s83, 0
	v_writelane_b32 v253, s0, 23
	s_nop 1
	v_writelane_b32 v253, s1, 24
	s_add_u32 s0, s82, 0xda5c000
	s_addc_u32 s1, s83, 0
	v_writelane_b32 v253, s0, 25
	s_cmpk_lt_i32 s25, 0x650
	s_nop 0
	v_writelane_b32 v253, s1, 26
	s_cselect_b64 s[0:1], -1, 0
	s_add_u32 s34, s82, 0xc634000
	v_writelane_b32 v253, s0, 27
	s_addc_u32 s35, s83, 0
	s_nop 0
	v_writelane_b32 v253, s1, 28
	s_add_u32 s0, s82, 0xbc34000
	s_addc_u32 s1, s83, 0
	v_writelane_b32 v253, s0, 29
	s_nop 1
	v_writelane_b32 v253, s1, 30
	s_add_u32 s0, s82, 0x9c60000
	s_addc_u32 s1, s83, 0
	v_writelane_b32 v253, s0, 31
	s_cmpk_lt_i32 s25, 0x380
	s_nop 0
	v_writelane_b32 v253, s1, 32
	s_cselect_b64 s[0:1], -1, 0
	v_writelane_b32 v253, s0, 33
	s_nop 1
	v_writelane_b32 v253, s1, 34
	s_add_u32 s0, s80, 0x6100000
	s_addc_u32 s1, s81, 0
	v_writelane_b32 v253, s0, 35
	s_nop 1
	v_writelane_b32 v253, s1, 36
	s_add_u32 s0, s82, 0x475d040
	s_addc_u32 s1, s83, 0
	v_writelane_b32 v253, s0, 37
	s_nop 1
	v_writelane_b32 v253, s1, 38
	s_add_u32 s0, s80, 0x7100000
	s_addc_u32 s1, s81, 0
	v_writelane_b32 v253, s0, 39
	s_nop 1
	v_writelane_b32 v253, s1, 40
	s_add_u32 s0, s80, 0x6000000
	s_addc_u32 s1, s81, 0
	v_writelane_b32 v253, s0, 41
	s_nop 1
	v_writelane_b32 v253, s1, 42
	s_add_u32 s0, s80, 0x5800000
	s_addc_u32 s1, s81, 0
	v_writelane_b32 v253, s0, 43
	s_cmpk_lt_i32 s25, 0x7f8
	s_nop 0
	v_writelane_b32 v253, s1, 44
	s_cselect_b64 s[0:1], -1, 0
	v_writelane_b32 v253, s0, 45
	s_nop 1
	v_writelane_b32 v253, s1, 46
	s_lshl_b32 s0, s26, 2
	v_writelane_b32 v253, s0, 47
	s_lshl_b32 s0, s25, 2
	v_writelane_b32 v253, s0, 48
	s_add_u32 s0, s82, 0xee61200
	s_addc_u32 s1, s83, 0
	s_add_u32 s48, s82, 0xee61400
	s_addc_u32 s49, s83, 0
	s_add_u32 s50, s82, 0xee61500
	s_addc_u32 s51, s83, 0
	s_add_u32 s52, s82, 0xee61600
	s_addc_u32 s53, s83, 0
	s_add_u32 s54, s82, 0xee61700
	s_addc_u32 s55, s83, 0
	s_add_u32 s56, s82, 0xee61800
	s_addc_u32 s57, s83, 0
	s_add_u32 s58, s82, 0xee61900
	s_addc_u32 s59, s83, 0
	s_add_u32 s60, s82, 0xee61a00
	v_writelane_b32 v253, s0, 49
	s_addc_u32 s61, s83, 0
	s_nop 0
	v_writelane_b32 v253, s1, 50
	s_add_u32 s0, s82, 0xee61b00
	s_addc_u32 s1, s83, 0
	v_writelane_b32 v253, s0, 51
	s_nop 1
	v_writelane_b32 v253, s1, 52
	s_add_u32 s0, s82, 0xee61c00
	s_addc_u32 s1, s83, 0
	v_writelane_b32 v253, s0, 53
	s_nop 1
	v_writelane_b32 v253, s1, 54
	s_add_u32 s0, s82, 0xee61d00
	s_addc_u32 s1, s83, 0
	v_writelane_b32 v253, s0, 55
	s_nop 1
	v_writelane_b32 v253, s1, 56
	s_add_u32 s0, s82, 0xee61e00
	s_addc_u32 s1, s83, 0
	v_writelane_b32 v253, s0, 57
	s_nop 1
	v_writelane_b32 v253, s1, 58
	s_add_u32 s0, s82, 0xee61f00
	s_addc_u32 s1, s83, 0
	v_writelane_b32 v253, s0, 59
	s_nop 1
	v_writelane_b32 v253, s1, 60
	s_add_u32 s0, s82, 0xee62000
	s_addc_u32 s1, s83, 0
	v_writelane_b32 v253, s0, 61
	s_nop 1
	v_writelane_b32 v253, s1, 62
	s_add_u32 s0, s82, 0xee62100
	s_addc_u32 s1, s83, 0
	v_writelane_b32 v253, s0, 63
	s_nop 1
	v_writelane_b32 v254, s1, 0
	s_add_u32 s0, s82, 0xee62200
	s_addc_u32 s1, s83, 0
	v_writelane_b32 v254, s0, 1
	s_nop 1
	v_writelane_b32 v254, s1, 2
	s_add_u32 s0, s82, 0xee62300
	s_addc_u32 s1, s83, 0
	v_writelane_b32 v254, s0, 3
	s_cmp_eq_u32 s20, 15
	s_nop 0
	v_writelane_b32 v254, s1, 4
	s_cselect_b64 s[0:1], -1, 0
	v_writelane_b32 v254, s0, 5
	s_cmp_eq_u32 s20, 14
	s_nop 0
	v_writelane_b32 v254, s1, 6
	s_cselect_b64 s[0:1], -1, 0
	v_writelane_b32 v254, s0, 7
	s_cmp_eq_u32 s20, 13
	s_nop 0
	v_writelane_b32 v254, s1, 8
	s_cselect_b64 s[0:1], -1, 0
	v_writelane_b32 v254, s0, 9
	s_cmp_eq_u32 s20, 12
	s_nop 0
	v_writelane_b32 v254, s1, 10
	s_cselect_b64 s[0:1], -1, 0
	v_writelane_b32 v254, s0, 11
	s_cmp_eq_u32 s20, 11
	s_nop 0
	v_writelane_b32 v254, s1, 12
	s_cselect_b64 s[0:1], -1, 0
	v_writelane_b32 v254, s0, 13
	s_cmp_eq_u32 s20, 10
	s_nop 0
	v_writelane_b32 v254, s1, 14
	s_cselect_b64 s[0:1], -1, 0
	v_writelane_b32 v254, s0, 15
	s_cmp_eq_u32 s20, 9
	s_nop 0
	v_writelane_b32 v254, s1, 16
	s_cselect_b64 s[0:1], -1, 0
	v_writelane_b32 v254, s0, 17
	s_cmp_eq_u32 s20, 8
	s_nop 0
	v_writelane_b32 v254, s1, 18
	s_cselect_b64 s[0:1], -1, 0
	v_writelane_b32 v254, s0, 19
	s_cmp_eq_u32 s20, 7
	s_nop 0
	v_writelane_b32 v254, s1, 20
	s_cselect_b64 s[0:1], -1, 0
	v_writelane_b32 v254, s0, 21
	s_cmp_eq_u32 s20, 6
	s_nop 0
	v_writelane_b32 v254, s1, 22
	s_cselect_b64 s[0:1], -1, 0
	v_writelane_b32 v254, s0, 23
	s_cmp_eq_u32 s20, 5
	s_nop 0
	v_writelane_b32 v254, s1, 24
	s_cselect_b64 s[0:1], -1, 0
	v_writelane_b32 v254, s0, 25
	s_cmp_eq_u32 s20, 4
	s_nop 0
	v_writelane_b32 v254, s1, 26
	s_cselect_b64 s[0:1], -1, 0
	v_writelane_b32 v254, s0, 27
	s_cmp_eq_u32 s20, 3
	s_nop 0
	v_writelane_b32 v254, s1, 28
	s_cselect_b64 s[0:1], -1, 0
	v_writelane_b32 v254, s0, 29
	s_cmp_eq_u32 s20, 2
	s_nop 0
	v_writelane_b32 v254, s1, 30
	s_cselect_b64 s[0:1], -1, 0
	v_writelane_b32 v254, s0, 31
	s_cmp_eq_u32 s20, 1
	s_nop 0
	v_writelane_b32 v254, s1, 32
	s_cselect_b64 s[0:1], -1, 0
	v_writelane_b32 v254, s0, 33
	s_cmp_eq_u32 s20, 0
	s_nop 0
	v_writelane_b32 v254, s1, 34
	s_cselect_b64 s[0:1], -1, 0
	v_writelane_b32 v254, s0, 35
	s_nop 1
	v_writelane_b32 v254, s1, 36
	s_lshl_b32 s0, s20, 8
	s_add_u32 s0, s30, s0
	s_addc_u32 s1, s31, 0
	s_add_u32 s20, s0, 0x1400
	s_addc_u32 s21, s1, 0
	v_writelane_b32 v254, s20, 37
	s_add_u32 s0, s0, 0x2400
	s_addc_u32 s1, s1, 0
	v_writelane_b32 v254, s21, 38
	v_writelane_b32 v254, s0, 39
	s_mov_b32 s30, s29
	s_mov_b32 s31, s29
	v_writelane_b32 v254, s1, 40
	s_add_u32 s0, s82, 0xee64400
	s_addc_u32 s1, s83, 0
	v_writelane_b32 v254, s0, 41
	v_mov_b64_e32 v[226:227], s[30:31]
	s_mov_b32 s20, 0x3f317217
	v_writelane_b32 v254, s1, 42
	s_add_u32 s0, s82, 0xee64500
	s_addc_u32 s1, s83, 0
	v_writelane_b32 v254, s0, 43
	s_mov_b32 s21, 0x7f800000
	v_mov_b64_e32 v[224:225], s[28:29]
	v_writelane_b32 v254, s1, 44
	s_movk_i32 s0, 0x3ff
	v_and_or_b32 v0, v0, s0, v208
	v_cmp_eq_u32_e64 s[0:1], 0, v0
	v_mbcnt_lo_u32_b32 v0, -1, 0
	v_mbcnt_hi_u32_b32 v212, -1, v0
	v_writelane_b32 v254, s0, 45
	s_nop 1
	v_writelane_b32 v254, s1, 46
	s_add_u32 s0, s82, 0x475d044
	s_addc_u32 s1, s83, 0
	v_writelane_b32 v254, s0, 47
	s_nop 1
	v_writelane_b32 v254, s1, 48
	s_add_u32 s0, s82, 0x475c044
	s_addc_u32 s1, s83, 0
	v_writelane_b32 v254, s0, 49
	s_nop 1
	v_writelane_b32 v254, s1, 50
	s_add_u32 s0, s82, 0xd60000
	v_writelane_b32 v254, s0, 51
	s_addc_u32 s0, s83, 0
	v_writelane_b32 v254, s0, 52
	s_sub_i32 s0, s25, s24
	v_writelane_b32 v254, s24, 53
	s_addk_i32 s0, 0xff3f
	v_writelane_b32 v254, s0, 54
	s_add_i32 s0, s25, 0xfffff148
	v_writelane_b32 v254, s0, 55
	s_lshl_b32 s0, s25, 8
	v_writelane_b32 v254, s0, 56
	s_lshl_b32 s0, s26, 8
	v_writelane_b32 v254, s0, 57
	s_lshl_b32 s0, s25, 4
	s_add_i32 s1, s0, 0xffffdc00
	v_writelane_b32 v254, s1, 58
	v_writelane_b32 v254, s3, 59
	s_lshl_b32 s1, s3, 4
	v_writelane_b32 v254, s1, 60
	s_addk_i32 s0, 0xd800
	v_writelane_b32 v254, s0, 61
	s_mov_b32 s0, s22
	s_ashr_i32 s23, s22, 31
	v_writelane_b32 v254, s0, 62
	s_mov_b32 s3, 0x800000
	s_nop 0
	v_writelane_b32 v254, s1, 63
	s_lshl_b64 s[0:1], s[22:23], 11
	v_writelane_b32 v255, s0, 0
	v_writelane_b32 v255, 0, 61
	v_writelane_b32 v255, 0, 62
	s_mov_b32 s23, 0xbfb8aa3b
	s_nop 0
	v_writelane_b32 v255, s1, 1
	s_lshl_b32 s0, s26, 3
	v_writelane_b32 v255, s0, 2
	v_writelane_b32 v255, s36, 3
	v_readlane_b32 s0, v251, 3
	s_mov_b32 s24, s0
	v_writelane_b32 v255, s37, 4
	v_writelane_b32 v255, s38, 5
	v_writelane_b32 v255, s39, 6
	v_writelane_b32 v255, s70, 7
	v_readlane_b32 s1, v251, 4
	s_nop 0
	v_writelane_b32 v255, s71, 8
	v_writelane_b32 v255, s42, 9
	s_nop 1
	v_writelane_b32 v255, s43, 10
	v_writelane_b32 v255, s48, 11
	s_nop 1
	v_writelane_b32 v255, s49, 12
	v_writelane_b32 v255, s50, 13
	s_nop 1
	v_writelane_b32 v255, s51, 14
	v_writelane_b32 v255, s52, 15
	s_nop 1
	v_writelane_b32 v255, s53, 16
	v_writelane_b32 v255, s54, 17
	s_nop 1
	v_writelane_b32 v255, s55, 18
	v_writelane_b32 v255, s56, 19
	s_nop 1
	v_writelane_b32 v255, s57, 20
	v_writelane_b32 v255, s58, 21
	s_nop 1
	v_writelane_b32 v255, s59, 22
	v_writelane_b32 v255, s60, 23
	s_nop 1
	v_writelane_b32 v255, s61, 24
	s_branch .LBB0_9

.LBB0_263:
	s_or_b64 exec, exec, s[40:41]
	s_ashr_i32 s40, s26, 6
	s_ashr_i32 s41, s40, 31
	s_lshl_b64 s[56:57], s[40:41], 7
	v_lshrrev_b32_e32 v5, 2, v1
	v_lshlrev_b32_e32 v4, 3, v3
	s_lshl_b64 s[56:57], s[56:57], s64
	v_lshlrev_b32_e32 v3, 5, v0
	v_and_b32_e32 v5, 8, v5
	v_and_b32_e32 v2, 3, v2
	s_lshl_b64 s[56:57], s[56:57], 1
	v_or3_b32 v2, v3, v5, v2
	s_add_u32 s56, s62, s56
	v_ashrrev_i32_e32 v3, 31, v2
	s_addc_u32 s57, s63, s57
	v_lshlrev_b64 v[2:3], s64, v[2:3]
	v_lshl_add_u64 v[2:3], v[2:3], 1, s[56:57]
	v_lshlrev_b32_e32 v128, 1, v4
	v_lshl_add_u64 v[48:49], v[2:3], 0, v[128:129]
	v_mad_u64_u32 v[2:3], s[56:57], v0, s84, v[42:43]
	v_add_u32_e32 v3, 0x2800, v2
	v_lshl_add_u64 v[50:51], v[48:49], 0, s[46:47]
	v_readfirstlane_b32 s26, v3
	v_add_u32_e32 v3, 0x2c00, v2
	s_mov_b32 m0, s26
	v_readfirstlane_b32 s26, v3
	v_add_u32_e32 v3, 0x3000, v2
	global_load_lds_dwordx4 v[48:49], off
	s_mov_b32 m0, s26
	v_readfirstlane_b32 s26, v3
	v_add_u32_e32 v2, 0x3400, v2
	global_load_lds_dwordx4 v[50:51], off
	v_lshl_add_u64 v[52:53], v[50:51], 0, s[52:53]
	s_mov_b32 m0, s26
	v_readfirstlane_b32 s26, v2
	global_load_lds_dwordx4 v[52:53], off
	v_lshl_add_u64 v[54:55], v[48:49], 0, s[48:49]
	s_mov_b32 m0, s26
	v_and_b32_e32 v2, 7, v1
	global_load_lds_dwordx4 v[54:55], off
	v_lshlrev_b32_e32 v3, 7, v1
	v_lshlrev_b32_e32 v2, 4, v2
	v_and_b32_e32 v3, 0x780, v3
	v_bitop3_b32 v1, v2, v1, 48 bitop3:0x78
	v_lshlrev_b32_e32 v57, 12, v0
	v_mov_b32_e32 v4, 0
	v_or_b32_e32 v43, v1, v3
	s_mov_b32 s28, 64
	v_bitop3_b32 v56, v1, 64, v3 bitop3:0x36
	v_add_u32_e32 v58, 0x2800, v57
	s_mov_b32 s41, 0
	s_mov_b32 s26, 0
	v_mov_b32_e32 v5, v4
	v_mov_b32_e32 v6, v4
	v_mov_b32_e32 v7, v4
	v_mov_b32_e32 v0, v4
	v_mov_b32_e32 v1, v4
	v_mov_b32_e32 v2, v4
	v_mov_b32_e32 v3, v4
	v_mov_b32_e32 v8, v4
	v_mov_b32_e32 v9, v4
	v_mov_b32_e32 v10, v4
	v_mov_b32_e32 v11, v4
	v_mov_b32_e32 v12, v4
	v_mov_b32_e32 v13, v4
	v_mov_b32_e32 v14, v4
	v_mov_b32_e32 v15, v4
	v_mov_b32_e32 v16, v4
	v_mov_b32_e32 v17, v4
	v_mov_b32_e32 v18, v4
	v_mov_b32_e32 v19, v4
	v_mov_b32_e32 v20, v4
	v_mov_b32_e32 v21, v4
	v_mov_b32_e32 v22, v4
	v_mov_b32_e32 v23, v4
	v_mov_b32_e32 v24, v4
	v_mov_b32_e32 v25, v4
	v_mov_b32_e32 v26, v4
	v_mov_b32_e32 v27, v4
	v_mov_b32_e32 v28, v4
	v_mov_b32_e32 v29, v4
	v_mov_b32_e32 v30, v4
	v_mov_b32_e32 v31, v4
	v_mov_b32_e32 v32, v4
	v_mov_b32_e32 v33, v4
	v_mov_b32_e32 v34, v4
	v_mov_b32_e32 v35, v4
	v_mov_b32_e32 v36, v4
	v_mov_b32_e32 v37, v4
	v_mov_b32_e32 v38, v4
	v_mov_b32_e32 v39, v4
	s_cmp_gt_u32 s65, 2
	s_cbranch_scc0 .Lr80_p1
	s_mov_b32 s71, 0x6800
	v_add_u32_e32 v59, s71, v42
	s_lshl_b64 s[56:57], s[28:29], 1
	v_readfirstlane_b32 s58, v59
	v_add_u32_e32 v62, 0x1000, v59
	v_lshl_add_u64 v[60:61], v[40:41], 0, s[56:57]
	s_mov_b32 m0, s58
	v_readfirstlane_b32 s58, v62
	global_load_lds_dwordx4 v[60:61], off
	v_lshl_add_u64 v[60:61], v[44:45], 0, s[56:57]
	s_mov_b32 m0, s58
	s_nop 0
	global_load_lds_dwordx4 v[60:61], off
	s_and_saveexec_b64 s[58:59], s[38:39]
	s_cbranch_execz .Lr80p_noA3
	v_add_u32_e32 v59, 0x2000, v59
	v_lshl_add_u64 v[60:61], s[28:29], 1, v[46:47]
	v_readfirstlane_b32 s72, v59
	s_mov_b32 m0, s72
	s_nop 0
	global_load_lds_dwordx4 v[60:61], off
.Lr80p_noA3:
	s_or_b64 exec, exec, s[58:59]
	v_add_u32_e32 v59, s71, v57
	v_add_u32_e32 v62, 0x2800, v59
	v_lshl_add_u64 v[60:61], v[48:49], 0, s[56:57]
	v_readfirstlane_b32 s58, v62
	v_add_u32_e32 v62, 0x2c00, v59
	s_mov_b32 m0, s58
	v_readfirstlane_b32 s58, v62
	v_add_u32_e32 v62, 0x3000, v59
	global_load_lds_dwordx4 v[60:61], off
	v_lshl_add_u64 v[60:61], v[50:51], 0, s[56:57]
	s_mov_b32 m0, s58
	v_readfirstlane_b32 s58, v62
	global_load_lds_dwordx4 v[60:61], off
	v_lshl_add_u64 v[60:61], v[52:53], 0, s[56:57]
	s_mov_b32 m0, s58
	v_add_u32_e32 v59, 0x3400, v59
	global_load_lds_dwordx4 v[60:61], off
	v_lshl_add_u64 v[60:61], v[54:55], 0, s[56:57]
	v_readfirstlane_b32 s56, v59
	s_mov_b32 m0, s56
	s_nop 0
	global_load_lds_dwordx4 v[60:61], off
	s_movk_i32 s28, 0x80
	s_mov_b32 s71, 0xd000
	v_add_u32_e32 v59, s71, v42
	s_lshl_b64 s[56:57], s[28:29], 1
	v_readfirstlane_b32 s58, v59
	v_add_u32_e32 v62, 0x1000, v59
	v_lshl_add_u64 v[60:61], v[40:41], 0, s[56:57]
	s_mov_b32 m0, s58
	v_readfirstlane_b32 s58, v62
	global_load_lds_dwordx4 v[60:61], off
	v_lshl_add_u64 v[60:61], v[44:45], 0, s[56:57]
	s_mov_b32 m0, s58
	s_nop 0
	global_load_lds_dwordx4 v[60:61], off
	s_and_saveexec_b64 s[58:59], s[38:39]
	s_cbranch_execz .Lr80q_noA3
	v_add_u32_e32 v59, 0x2000, v59
	v_lshl_add_u64 v[60:61], s[28:29], 1, v[46:47]
	v_readfirstlane_b32 s72, v59
	s_mov_b32 m0, s72
	s_nop 0
	global_load_lds_dwordx4 v[60:61], off
.Lr80q_noA3:
	s_or_b64 exec, exec, s[58:59]
	v_add_u32_e32 v59, s71, v57
	v_add_u32_e32 v62, 0x2800, v59
	v_lshl_add_u64 v[60:61], v[48:49], 0, s[56:57]
	v_readfirstlane_b32 s58, v62
	v_add_u32_e32 v62, 0x2c00, v59
	s_mov_b32 m0, s58
	v_readfirstlane_b32 s58, v62
	v_add_u32_e32 v62, 0x3000, v59
	global_load_lds_dwordx4 v[60:61], off
	v_lshl_add_u64 v[60:61], v[50:51], 0, s[56:57]
	s_mov_b32 m0, s58
	v_readfirstlane_b32 s58, v62
	global_load_lds_dwordx4 v[60:61], off
	v_lshl_add_u64 v[60:61], v[52:53], 0, s[56:57]
	s_mov_b32 m0, s58
	v_add_u32_e32 v59, 0x3400, v59
	global_load_lds_dwordx4 v[60:61], off
	v_lshl_add_u64 v[60:61], v[54:55], 0, s[56:57]
	v_readfirstlane_b32 s56, v59
	s_mov_b32 m0, s56
	s_nop 0
	global_load_lds_dwordx4 v[60:61], off
.Lr80_p1:
	s_movk_i32 s28, 0xc0
.LBB0_266:
	s_add_i32 s58, s26, 2
	s_cmp_lt_u32 s58, s65
	s_cbranch_scc1 .Lr80_c2
	s_add_i32 s58, s26, 1
	s_cmp_lt_u32 s58, s65
	s_cbranch_scc1 .Lr80_c1
	s_waitcnt vmcnt(0)
	s_branch .Lr80_wd
.Lr80_c2:
	s_cmp_lg_u64 s[38:39], 0
	s_cbranch_scc1 .Lr80_w14
	s_waitcnt vmcnt(12)
	s_branch .Lr80_wd
.Lr80_w14:
	s_waitcnt vmcnt(14)
	s_branch .Lr80_wd

.Lr80_wd:
	s_waitcnt lgkmcnt(0)
	s_barrier
	v_add_u32_e32 v60, s41, v58
	v_add_u32_e32 v59, s41, v43
	v_add_u32_e32 v116, s41, v56
	v_add_u32_e32 v117, v60, v43
	v_add_u32_e32 v118, v60, v56
	ds_read_b128 v[60:63], v59
	ds_read_b128 v[64:67], v59 offset:2048
	ds_read_b128 v[68:71], v59 offset:4096
	ds_read_b128 v[72:75], v59 offset:6144
	ds_read_b128 v[76:79], v59 offset:8192
	ds_read_b128 v[80:83], v117
	ds_read_b128 v[84:87], v117 offset:2048
	ds_read_b128 v[88:91], v116
	ds_read_b128 v[92:95], v116 offset:2048
	ds_read_b128 v[96:99], v116 offset:4096
	ds_read_b128 v[100:103], v116 offset:6144
	ds_read_b128 v[104:107], v116 offset:8192
	ds_read_b128 v[108:111], v118
	ds_read_b128 v[112:115], v118 offset:2048
	s_waitcnt lgkmcnt(7)
	v_mfma_f32_16x16x32_bf16 v[36:39], v[80:83], v[60:63], v[36:39]
	v_mfma_f32_16x16x32_bf16 v[32:35], v[84:87], v[60:63], v[32:35]
	v_mfma_f32_16x16x32_bf16 v[28:31], v[80:83], v[64:67], v[28:31]
	v_mfma_f32_16x16x32_bf16 v[24:27], v[84:87], v[64:67], v[24:27]
	v_mfma_f32_16x16x32_bf16 v[20:23], v[80:83], v[68:71], v[20:23]
	v_mfma_f32_16x16x32_bf16 v[16:19], v[84:87], v[68:71], v[16:19]
	v_mfma_f32_16x16x32_bf16 v[12:15], v[80:83], v[72:75], v[12:15]
	v_mfma_f32_16x16x32_bf16 v[0:3], v[80:83], v[76:79], v[0:3]
	v_mfma_f32_16x16x32_bf16 v[4:7], v[84:87], v[76:79], v[4:7]
	v_mfma_f32_16x16x32_bf16 v[8:11], v[84:87], v[72:75], v[8:11]
	s_waitcnt lgkmcnt(0)
	s_barrier
	s_add_i32 s58, s26, 3
	s_cmp_lt_u32 s58, s65
	s_cbranch_scc0 .Lr80_nd
	s_mov_b32 s71, s41
	v_add_u32_e32 v59, s71, v42
	s_lshl_b64 s[56:57], s[28:29], 1
	v_readfirstlane_b32 s58, v59
	v_add_u32_e32 v62, 0x1000, v59
	v_lshl_add_u64 v[60:61], v[40:41], 0, s[56:57]
	s_mov_b32 m0, s58
	v_readfirstlane_b32 s58, v62
	global_load_lds_dwordx4 v[60:61], off
	v_lshl_add_u64 v[60:61], v[44:45], 0, s[56:57]
	s_mov_b32 m0, s58
	s_nop 0
	global_load_lds_dwordx4 v[60:61], off
	s_and_saveexec_b64 s[58:59], s[38:39]
	s_cbranch_execz .Lr80i_noA3
	v_add_u32_e32 v59, 0x2000, v59
	v_lshl_add_u64 v[60:61], s[28:29], 1, v[46:47]
	v_readfirstlane_b32 s72, v59
	s_mov_b32 m0, s72
	s_nop 0
	global_load_lds_dwordx4 v[60:61], off

.Lr80_nd:
	s_nop 0
	v_mfma_f32_16x16x32_bf16 v[36:39], v[108:111], v[88:91], v[36:39]
	v_mfma_f32_16x16x32_bf16 v[32:35], v[112:115], v[88:91], v[32:35]
	v_mfma_f32_16x16x32_bf16 v[28:31], v[108:111], v[92:95], v[28:31]
	v_mfma_f32_16x16x32_bf16 v[24:27], v[112:115], v[92:95], v[24:27]
	v_mfma_f32_16x16x32_bf16 v[20:23], v[108:111], v[96:99], v[20:23]
	v_mfma_f32_16x16x32_bf16 v[16:19], v[112:115], v[96:99], v[16:19]
	v_mfma_f32_16x16x32_bf16 v[12:15], v[108:111], v[100:103], v[12:15]
	v_mfma_f32_16x16x32_bf16 v[8:11], v[112:115], v[100:103], v[8:11]
	v_mfma_f32_16x16x32_bf16 v[0:3], v[108:111], v[104:107], v[0:3]
	v_mfma_f32_16x16x32_bf16 v[4:7], v[112:115], v[104:107], v[4:7]
	s_add_i32 s26, s26, 1
	s_add_i32 s28, s28, 64
	s_add_i32 s41, s41, 0x6800
	s_cmp_eq_u32 s41, 0x13800
	s_cselect_b32 s41, 0, s41
	s_cmp_lg_u32 s26, s65
	s_cbranch_scc1 .LBB0_266

.LBB0_456:
	v_readlane_b32 s25, v255, 43
	v_readlane_b32 s0, v251, 3
	s_add_i32 s24, s25, 1
	v_readlane_b32 s1, v251, 4
	v_readlane_b32 s48, v255, 11
	v_readlane_b32 s50, v255, 13
	v_readlane_b32 s52, v255, 15
	v_readlane_b32 s54, v255, 17
	v_readlane_b32 s56, v255, 19
	v_readlane_b32 s58, v255, 21
	v_readlane_b32 s60, v255, 23
	s_cmp_ge_i32 s24, s1
	s_mov_b64 s[0:1], -1
	v_readlane_b32 s42, v255, 9
	v_readlane_b32 s49, v255, 12
	v_readlane_b32 s51, v255, 14
	v_readlane_b32 s53, v255, 16
	v_readlane_b32 s55, v255, 18
	v_readlane_b32 s57, v255, 20
	v_readlane_b32 s59, v255, 22
	v_readlane_b32 s61, v255, 24
	v_readlane_b32 s43, v255, 10
	s_cbranch_scc1 .LBB0_8
	v_readlane_b32 s0, v251, 3
	v_readlane_b32 s1, v251, 4
	s_cmp_lg_u32 s25, s0
	s_mov_b64 s[0:1], -1
	s_cbranch_scc0 .LBB0_511
	s_waitcnt vmcnt(0)
	v_mov_b32_e32 v0, v208
	s_waitcnt vmcnt(0) lgkmcnt(0)
	s_barrier
	s_nop 0
	v_cmp_eq_u32_e32 vcc, 0, v0
	s_and_saveexec_b64 s[0:1], vcc
	s_cbranch_execz .LBB0_510
	s_mov_b64 s[26:27], src_shared_base
	v_mov_b32_e32 v131, s27
	s_waitcnt vmcnt(0) expcnt(0) lgkmcnt(0)
	v_readlane_b32 s25, v255, 61
	v_readlane_b32 s26, v255, 62
	v_mov_b32_e32 v133, s27
	s_nop 0
	v_mov_b32_e32 v2, s25
	v_mov_b32_e32 v0, s26
	s_nop 0
	v_cmp_eq_u32_e32 vcc, 0, v2
	s_and_saveexec_b64 s[30:31], vcc
	s_cbranch_execz .LBB0_474
	s_mov_b32 s25, 1
	s_mov_b32 s27, s22
	s_branch .LBB0_462

.LBB0_473:
	v_readlane_b32 s26, v254, 35
	v_readlane_b32 s27, v254, 36
	v_cmp_ne_u32_e32 vcc, 0, v6
	s_mov_b64 s[36:37], src_shared_base
	v_cndmask_b32_e64 v16, 0, v6, s[26:27]
	v_readlane_b32 s26, v254, 33
	v_readlane_b32 s27, v254, 34
	v_cndmask_b32_e64 v6, 0, 1, vcc
	v_cmp_ne_u32_e32 vcc, 0, v0
	v_cndmask_b32_e64 v16, v16, v0, s[26:27]
	v_readlane_b32 s26, v254, 31
	v_readlane_b32 s27, v254, 32
	v_addc_co_u32_e32 v0, vcc, 0, v6, vcc
	s_nop 0
	v_cndmask_b32_e64 v16, v16, v1, s[26:27]
	v_readlane_b32 s26, v254, 29
	v_readlane_b32 s27, v254, 30
	v_cmp_ne_u32_e32 vcc, 0, v1
	v_mov_b32_e32 v131, s37
	v_cndmask_b32_e64 v16, v16, v2, s[26:27]
	v_readlane_b32 s26, v254, 27
	v_readlane_b32 s27, v254, 28
	v_cndmask_b32_e64 v1, 0, 1, vcc
	v_cmp_ne_u32_e32 vcc, 0, v2
	v_cndmask_b32_e64 v16, v16, v3, s[26:27]
	v_readlane_b32 s26, v254, 25
	v_readlane_b32 s27, v254, 26
	v_addc_co_u32_e32 v0, vcc, v0, v1, vcc
	s_nop 0
	v_cndmask_b32_e64 v16, v16, v4, s[26:27]
	v_readlane_b32 s26, v254, 23
	v_readlane_b32 s27, v254, 24
	v_cmp_ne_u32_e32 vcc, 0, v3
	v_mov_b32_e32 v133, s37
	v_cndmask_b32_e64 v16, v16, v5, s[26:27]
	v_readlane_b32 s26, v254, 21
	v_readlane_b32 s27, v254, 22
	v_cndmask_b32_e64 v1, 0, 1, vcc
	v_cmp_ne_u32_e32 vcc, 0, v4
	v_cndmask_b32_e64 v16, v16, v7, s[26:27]
	v_readlane_b32 s26, v254, 19
	v_readlane_b32 s27, v254, 20
	v_addc_co_u32_e32 v0, vcc, v0, v1, vcc
	s_nop 0
	v_cndmask_b32_e64 v16, v16, v8, s[26:27]
	v_readlane_b32 s26, v254, 17
	v_cmp_ne_u32_e32 vcc, 0, v5
	v_readlane_b32 s27, v254, 18
	s_nop 0
	v_cndmask_b32_e64 v1, 0, 1, vcc
	v_cmp_ne_u32_e32 vcc, 0, v7
	v_cndmask_b32_e64 v16, v16, v9, s[26:27]
	v_readlane_b32 s26, v254, 15
	v_addc_co_u32_e32 v0, vcc, v0, v1, vcc
	v_readlane_b32 s27, v254, 16
	v_cmp_ne_u32_e32 vcc, 0, v8
	s_nop 0
	v_cndmask_b32_e64 v16, v16, v10, s[26:27]
	v_readlane_b32 s26, v254, 13
	v_cndmask_b32_e64 v1, 0, 1, vcc
	v_cmp_ne_u32_e32 vcc, 0, v9
	v_readlane_b32 s27, v254, 14
	s_nop 0
	v_addc_co_u32_e32 v0, vcc, v0, v1, vcc
	v_cndmask_b32_e64 v16, v16, v11, s[26:27]
	v_readlane_b32 s26, v254, 11
	v_cmp_ne_u32_e32 vcc, 0, v10
	v_readlane_b32 s27, v254, 12
	s_nop 0
	v_cndmask_b32_e64 v1, 0, 1, vcc
	v_cmp_ne_u32_e32 vcc, 0, v11
	v_cndmask_b32_e64 v16, v16, v12, s[26:27]
	v_readlane_b32 s26, v254, 9
	v_addc_co_u32_e32 v0, vcc, v0, v1, vcc
	v_readlane_b32 s27, v254, 10
	v_cmp_ne_u32_e32 vcc, 0, v12
	s_nop 0
	v_cndmask_b32_e64 v16, v16, v13, s[26:27]
	v_readlane_b32 s26, v254, 7
	v_cndmask_b32_e64 v1, 0, 1, vcc
	v_cmp_ne_u32_e32 vcc, 0, v13
	v_readlane_b32 s27, v254, 8
	s_nop 0
	v_addc_co_u32_e32 v0, vcc, v0, v1, vcc
	v_cndmask_b32_e64 v16, v16, v14, s[26:27]
	v_readlane_b32 s26, v254, 5
	v_cmp_ne_u32_e32 vcc, 0, v14
	v_readlane_b32 s27, v254, 6
	s_nop 0
	v_cndmask_b32_e64 v1, 0, 1, vcc
	v_cmp_ne_u32_e32 vcc, 0, v15
	v_cndmask_b32_e64 v16, v16, v15, s[26:27]
	v_max_u32_e32 v2, 1, v16
	v_addc_co_u32_e32 v0, vcc, v0, v1, vcc
	v_max_u32_e32 v0, 1, v0
	s_nop 0
	v_readfirstlane_b32 s26, v2
	v_readfirstlane_b32 s27, v0
	s_nop 1
	v_writelane_b32 v255, s26, 61
	v_writelane_b32 v255, s27, 62

	.amdhsa_kernel _Z4mega6Paramsii
		.amdhsa_group_segment_fixed_size 81920
		.amdhsa_private_segment_fixed_size 0
		.amdhsa_kernarg_size 552
		.amdhsa_user_sgpr_count 2
		.amdhsa_user_sgpr_dispatch_ptr 0
		.amdhsa_user_sgpr_queue_ptr 0
		.amdhsa_user_sgpr_kernarg_segment_ptr 1
		.amdhsa_user_sgpr_dispatch_id 0
		.amdhsa_user_sgpr_kernarg_preload_length 0
		.amdhsa_user_sgpr_kernarg_preload_offset 0
		.amdhsa_user_sgpr_private_segment_size 0
		.amdhsa_uses_dynamic_stack 0
		.amdhsa_enable_private_segment 0
		.amdhsa_system_sgpr_workgroup_id_x 1
		.amdhsa_system_sgpr_workgroup_id_y 0
		.amdhsa_system_sgpr_workgroup_id_z 0
		.amdhsa_system_sgpr_workgroup_info 0
		.amdhsa_system_vgpr_workitem_id 2
		.amdhsa_next_free_vgpr 256
		.amdhsa_next_free_sgpr 100
		.amdhsa_accum_offset 256
		.amdhsa_reserve_vcc 1
		.amdhsa_float_round_mode_32 0
		.amdhsa_float_round_mode_16_64 0
		.amdhsa_float_denorm_mode_32 3
		.amdhsa_float_denorm_mode_16_64 3
		.amdhsa_dx10_clamp 1
		.amdhsa_ieee_mode 1
		.amdhsa_fp16_overflow 0
		.amdhsa_tg_split 0
		.amdhsa_exception_fp_ieee_invalid_op 0
		.amdhsa_exception_fp_denorm_src 0
		.amdhsa_exception_fp_ieee_div_zero 0
		.amdhsa_exception_fp_ieee_overflow 0
		.amdhsa_exception_fp_ieee_underflow 0
		.amdhsa_exception_fp_ieee_inexact 0
		.amdhsa_exception_int_div_zero 0
	.end_amdhsa_kernel

amdhsa.kernels:
  - .agpr_count:     0
    .args:
      - .offset:         0
        .size:           288
        .value_kind:     by_value
      - .offset:         288
        .size:           4
        .value_kind:     by_value
      - .offset:         292
        .size:           4
        .value_kind:     by_value
      - .offset:         296
        .size:           4
        .value_kind:     hidden_block_count_x
      - .offset:         300
        .size:           4
        .value_kind:     hidden_block_count_y
      - .offset:         304
        .size:           4
        .value_kind:     hidden_block_count_z
      - .offset:         308
        .size:           2
        .value_kind:     hidden_group_size_x
      - .offset:         310
        .size:           2
        .value_kind:     hidden_group_size_y
      - .offset:         312
        .size:           2
        .value_kind:     hidden_group_size_z
      - .offset:         314
        .size:           2
        .value_kind:     hidden_remainder_x
      - .offset:         316
        .size:           2
        .value_kind:     hidden_remainder_y
      - .offset:         318
        .size:           2
        .value_kind:     hidden_remainder_z
      - .offset:         336
        .size:           8
        .value_kind:     hidden_global_offset_x
      - .offset:         344
        .size:           8
        .value_kind:     hidden_global_offset_y
      - .offset:         352
        .size:           8
        .value_kind:     hidden_global_offset_z
      - .offset:         360
        .size:           2
        .value_kind:     hidden_grid_dims
      - .offset:         384
        .size:           8
        .value_kind:     hidden_multigrid_sync_arg
    .group_segment_fixed_size: 81920
    .kernarg_segment_align: 8
    .kernarg_segment_size: 552
    .language:       OpenCL C
    .language_version:
      - 2
      - 0
    .max_flat_workgroup_size: 256
    .name:           _Z4mega6Paramsii
    .private_segment_fixed_size: 0
    .sgpr_count:     106
    .sgpr_spill_count: 329
    .symbol:         _Z4mega6Paramsii.kd
    .uniform_work_group_size: 1
    .uses_dynamic_stack: false
    .vgpr_count:     256
    .vgpr_spill_count: 0
    .wavefront_size: 64
